# v80 + fused ResidNorm epilogues (out-proj, FFN2): the 32 f32 residual stores issued before the cross-workgroup statistic exchange (they do not depend on it); four vacuous vmcnt waits after the exchang
# speedup vs baseline: 1.0106x; 1.0096x over previous
.LBB0_112:
	s_or_b64 exec, exec, s[10:11]
	v_readlane_b32 s10, v255, 20
	s_add_u32 s10, s10, s6
	v_readlane_b32 s11, v255, 38
	s_addc_u32 s11, s11, s7
	s_nop 0
	v_lshl_add_u64 v[64:65], s[10:11], 0, v[230:231]
	v_readlane_b32 s10, v255, 43
	s_add_u32 s6, s10, s6
	v_readlane_b32 s10, v255, 44
	s_addc_u32 s7, s10, s7
	v_lshl_add_u64 v[68:69], s[6:7], 0, v[230:231]
	global_load_dwordx4 v[88:91], v[64:65], off
	global_load_dwordx4 v[80:83], v[64:65], off offset:64
	global_load_dwordx4 v[92:95], v[68:69], off
	global_load_dwordx4 v[84:87], v[68:69], off offset:64
	global_load_dwordx4 v[72:75], v[64:65], off offset:512
	s_nop 0
	global_load_dwordx4 v[64:67], v[64:65], off offset:576
	s_nop 0
	global_load_dwordx4 v[76:79], v[68:69], off offset:512
	s_nop 0
	global_load_dwordx4 v[68:71], v[68:69], off offset:576
	s_and_b64 s[98:99], s[4:5], exec
	v_readlane_b32 s98, v254, 24
	v_readlane_b32 s99, v254, 26
	s_cselect_b32 s98, s98, s99
	v_readlane_b32 s99, v254, 25
	v_readlane_b32 s101, v254, 27
	s_cselect_b32 s99, s99, s101
	v_lshl_add_u64 v[166:167], v[226:227], 2, s[98:99]
	v_lshl_add_u64 v[166:167], v[166:167], 0, v[228:229]
	global_store_dwordx4 v[166:167], v[128:131], off
	global_store_dwordx4 v[166:167], v[132:135], off offset:64
	global_store_dwordx4 v[166:167], v[136:139], off offset:512
	global_store_dwordx4 v[166:167], v[140:143], off offset:576
	s_mov_b32 s98, 0x10000
	s_mov_b32 s99, 0
	v_lshl_add_u64 v[168:169], v[166:167], 0, s[98:99]
	global_store_dwordx4 v[168:169], v[144:147], off
	global_store_dwordx4 v[168:169], v[148:151], off offset:64
	global_store_dwordx4 v[168:169], v[152:155], off offset:512
	global_store_dwordx4 v[168:169], v[156:159], off offset:576
	v_lshl_add_u64 v[168:169], v[168:169], 0, s[98:99]
	global_store_dwordx4 v[168:169], v[112:115], off
	global_store_dwordx4 v[168:169], v[116:119], off offset:64
	global_store_dwordx4 v[168:169], v[120:123], off offset:512
	global_store_dwordx4 v[168:169], v[124:127], off offset:576
	v_lshl_add_u64 v[168:169], v[168:169], 0, s[98:99]
	global_store_dwordx4 v[168:169], v[96:99], off
	global_store_dwordx4 v[168:169], v[100:103], off offset:64
	global_store_dwordx4 v[168:169], v[104:107], off offset:512
	global_store_dwordx4 v[168:169], v[108:111], off offset:576
	s_and_b64 vcc, exec, s[48:49]
	s_cbranch_vccnz .Lx1skip_a
	s_mov_b32 s98, 0x80000
	v_lshl_add_u64 v[166:167], v[166:167], 0, s[98:99]
	global_store_dwordx4 v[166:167], v[60:63], off
	global_store_dwordx4 v[166:167], v[56:59], off offset:64
	global_store_dwordx4 v[166:167], v[52:55], off offset:512
	global_store_dwordx4 v[166:167], v[48:51], off offset:576
	s_mov_b32 s98, 0x10000
	v_lshl_add_u64 v[168:169], v[166:167], 0, s[98:99]
	global_store_dwordx4 v[168:169], v[44:47], off
	global_store_dwordx4 v[168:169], v[40:43], off offset:64
	global_store_dwordx4 v[168:169], v[36:39], off offset:512
	global_store_dwordx4 v[168:169], v[32:35], off offset:576
	v_lshl_add_u64 v[168:169], v[168:169], 0, s[98:99]
	global_store_dwordx4 v[168:169], v[28:31], off
	global_store_dwordx4 v[168:169], v[24:27], off offset:64
	global_store_dwordx4 v[168:169], v[20:23], off offset:512
	global_store_dwordx4 v[168:169], v[16:19], off offset:576
	v_lshl_add_u64 v[168:169], v[168:169], 0, s[98:99]
	global_store_dwordx4 v[168:169], v[12:15], off
	global_store_dwordx4 v[168:169], v[8:11], off offset:64
	global_store_dwordx4 v[168:169], v[4:7], off offset:512
	global_store_dwordx4 v[168:169], v[0:3], off offset:576
.Lx1skip_a:
	s_mov_b64 s[6:7], exec
	v_readlane_b32 s10, v255, 53
	v_readlane_b32 s11, v255, 54
	s_and_b64 s[10:11], s[6:7], s[10:11]
	v_readlane_b32 s12, v255, 22
	v_readlane_b32 s13, v255, 23
	s_mov_b64 exec, s[10:11]
	s_cbranch_execz .LBB0_117
	v_mov_b32_e32 v160, 0xfffff
	s_branch .LBB0_115

.LBB0_119:
	s_or_b64 exec, exec, s[6:7]
	s_and_b64 s[0:1], s[4:5], exec
	v_readlane_b32 s4, v254, 24
	s_waitcnt vmcnt(0) lgkmcnt(0)
	s_barrier
	v_readlane_b32 s5, v254, 25
	v_readlane_b32 s0, v254, 27
	v_readlane_b32 s1, v254, 26
	ds_read_b32 v160, v249
	s_cselect_b32 s0, s5, s0
	s_cselect_b32 s1, s4, s1
	v_mov_b32_e32 v162, s1
	v_mov_b32_e32 v163, s0
	v_lshl_add_u64 v[162:163], v[226:227], 2, v[162:163]
	v_lshl_add_u64 v[164:165], s[2:3], 0, v[198:199]
	v_lshl_add_u64 v[168:169], v[162:163], 0, v[228:229]
	v_lshlrev_b64 v[164:165], 11, v[164:165]
	v_lshl_add_u64 v[166:167], s[18:19], 0, v[164:165]
	v_lshlrev_b64 v[164:165], 1, v[226:227]
	s_waitcnt lgkmcnt(0)
	v_pk_mul_f32 v[130:131], v[130:131], v[160:161] op_sel_hi:[1,0]
	v_pk_mul_f32 v[128:129], v[128:129], v[160:161] op_sel_hi:[1,0]
	v_pk_fma_f32 v[130:131], v[90:91], v[130:131], v[94:95]
	v_pk_fma_f32 v[128:129], v[88:89], v[128:129], v[92:93]
	v_lshl_add_u64 v[166:167], v[166:167], 0, v[164:165]
	v_cvt_pk_bf16_f32 v128, v128, v129
	v_cvt_pk_bf16_f32 v129, v130, v131
	global_store_dwordx2 v[166:167], v[128:129], off
	v_pk_mul_f32 v[128:129], v[134:135], v[160:161] op_sel_hi:[1,0]
	v_pk_mul_f32 v[130:131], v[132:133], v[160:161] op_sel_hi:[1,0]
	v_pk_fma_f32 v[128:129], v[82:83], v[128:129], v[86:87]
	v_pk_fma_f32 v[130:131], v[80:81], v[130:131], v[84:85]
	v_readlane_b32 s0, v254, 4
	v_cvt_pk_bf16_f32 v130, v130, v131
	v_cvt_pk_bf16_f32 v131, v128, v129
	global_store_dwordx2 v[166:167], v[130:131], off offset:32
	v_pk_mul_f32 v[128:129], v[138:139], v[160:161] op_sel_hi:[1,0]
	v_pk_mul_f32 v[130:131], v[136:137], v[160:161] op_sel_hi:[1,0]
	v_pk_fma_f32 v[128:129], v[74:75], v[128:129], v[78:79]
	v_pk_fma_f32 v[130:131], v[72:73], v[130:131], v[76:77]
	v_or_b32_e32 v132, 16, v224
	v_cvt_pk_bf16_f32 v130, v130, v131
	v_cvt_pk_bf16_f32 v131, v128, v129
	global_store_dwordx2 v[166:167], v[130:131], off offset:256
	v_pk_mul_f32 v[128:129], v[142:143], v[160:161] op_sel_hi:[1,0]
	v_pk_mul_f32 v[130:131], v[140:141], v[160:161] op_sel_hi:[1,0]
	v_pk_fma_f32 v[128:129], v[66:67], v[128:129], v[70:71]
	v_pk_fma_f32 v[130:131], v[64:65], v[130:131], v[68:69]
	v_ashrrev_i32_e32 v133, 31, v132
	v_cvt_pk_bf16_f32 v130, v130, v131
	v_cvt_pk_bf16_f32 v131, v128, v129
	v_lshl_add_u32 v128, v208, 2, s0
	ds_read_b32 v128, v128
	global_store_dwordx2 v[166:167], v[130:131], off offset:288
	v_lshl_add_u64 v[130:131], s[2:3], 0, v[208:209]
	v_lshlrev_b64 v[130:131], 11, v[130:131]
	v_lshl_add_u64 v[130:131], s[18:19], 0, v[130:131]
	s_waitcnt lgkmcnt(0)
	v_pk_mul_f32 v[134:135], v[146:147], v[128:129] op_sel_hi:[1,0]
	v_pk_mul_f32 v[136:137], v[144:145], v[128:129] op_sel_hi:[1,0]
	v_lshlrev_b64 v[132:133], 12, v[132:133]
	v_pk_fma_f32 v[134:135], v[90:91], v[134:135], v[94:95]
	v_pk_fma_f32 v[136:137], v[88:89], v[136:137], v[92:93]
	v_lshl_add_u64 v[130:131], v[130:131], 0, v[164:165]
	v_lshl_add_u64 v[132:133], v[162:163], 0, v[132:133]
	v_cvt_pk_bf16_f32 v136, v136, v137
	v_cvt_pk_bf16_f32 v137, v134, v135
	global_store_dwordx2 v[130:131], v[136:137], off
	v_pk_mul_f32 v[134:135], v[150:151], v[128:129] op_sel_hi:[1,0]
	v_pk_mul_f32 v[136:137], v[148:149], v[128:129] op_sel_hi:[1,0]
	v_pk_fma_f32 v[134:135], v[82:83], v[134:135], v[86:87]
	v_pk_fma_f32 v[136:137], v[80:81], v[136:137], v[84:85]
	s_and_b64 vcc, exec, s[48:49]
	v_cvt_pk_bf16_f32 v136, v136, v137
	v_cvt_pk_bf16_f32 v137, v134, v135
	global_store_dwordx2 v[130:131], v[136:137], off offset:32
	v_pk_mul_f32 v[134:135], v[154:155], v[128:129] op_sel_hi:[1,0]
	v_pk_mul_f32 v[136:137], v[152:153], v[128:129] op_sel_hi:[1,0]
	v_pk_fma_f32 v[134:135], v[74:75], v[134:135], v[78:79]
	v_pk_fma_f32 v[136:137], v[72:73], v[136:137], v[76:77]
	s_nop 0
	v_cvt_pk_bf16_f32 v136, v136, v137
	v_cvt_pk_bf16_f32 v137, v134, v135
	global_store_dwordx2 v[130:131], v[136:137], off offset:256
	v_pk_mul_f32 v[132:133], v[158:159], v[128:129] op_sel_hi:[1,0]
	v_pk_mul_f32 v[128:129], v[156:157], v[128:129] op_sel_hi:[1,0]
	v_pk_fma_f32 v[132:133], v[66:67], v[132:133], v[70:71]
	v_pk_fma_f32 v[128:129], v[64:65], v[128:129], v[68:69]
	s_nop 0
	v_cvt_pk_bf16_f32 v128, v128, v129
	v_cvt_pk_bf16_f32 v129, v132, v133
	global_store_dwordx2 v[130:131], v[128:129], off offset:288
	v_lshl_add_u32 v128, v210, 2, s0
	ds_read_b32 v128, v128
	v_or_b32_e32 v132, 32, v224
	v_ashrrev_i32_e32 v133, 31, v132
	v_lshlrev_b64 v[132:133], 12, v[132:133]
	v_lshl_add_u64 v[130:131], s[2:3], 0, v[210:211]
	v_lshl_add_u64 v[132:133], v[162:163], 0, v[132:133]
	v_lshlrev_b64 v[130:131], 11, v[130:131]
	v_lshl_add_u64 v[130:131], s[18:19], 0, v[130:131]
	v_lshl_add_u64 v[130:131], v[130:131], 0, v[164:165]
	s_waitcnt lgkmcnt(0)
	v_pk_mul_f32 v[114:115], v[114:115], v[128:129] op_sel_hi:[1,0]
	v_pk_mul_f32 v[112:113], v[112:113], v[128:129] op_sel_hi:[1,0]
	v_pk_fma_f32 v[114:115], v[90:91], v[114:115], v[94:95]
	v_pk_fma_f32 v[112:113], v[88:89], v[112:113], v[92:93]
	s_nop 0
	v_cvt_pk_bf16_f32 v112, v112, v113
	v_cvt_pk_bf16_f32 v113, v114, v115
	global_store_dwordx2 v[130:131], v[112:113], off
	v_pk_mul_f32 v[112:113], v[118:119], v[128:129] op_sel_hi:[1,0]
	v_pk_mul_f32 v[114:115], v[116:117], v[128:129] op_sel_hi:[1,0]
	v_pk_fma_f32 v[112:113], v[82:83], v[112:113], v[86:87]
	v_pk_fma_f32 v[114:115], v[80:81], v[114:115], v[84:85]
	v_or_b32_e32 v116, 48, v224
	v_cvt_pk_bf16_f32 v114, v114, v115
	v_cvt_pk_bf16_f32 v115, v112, v113
	global_store_dwordx2 v[130:131], v[114:115], off offset:32
	v_pk_mul_f32 v[112:113], v[122:123], v[128:129] op_sel_hi:[1,0]
	v_pk_mul_f32 v[114:115], v[120:121], v[128:129] op_sel_hi:[1,0]
	v_pk_fma_f32 v[112:113], v[74:75], v[112:113], v[78:79]
	v_pk_fma_f32 v[114:115], v[72:73], v[114:115], v[76:77]
	v_ashrrev_i32_e32 v117, 31, v116
	v_cvt_pk_bf16_f32 v114, v114, v115
	v_cvt_pk_bf16_f32 v115, v112, v113
	global_store_dwordx2 v[130:131], v[114:115], off offset:256
	v_pk_mul_f32 v[112:113], v[126:127], v[128:129] op_sel_hi:[1,0]
	v_pk_mul_f32 v[114:115], v[124:125], v[128:129] op_sel_hi:[1,0]
	v_pk_fma_f32 v[112:113], v[66:67], v[112:113], v[70:71]
	v_pk_fma_f32 v[114:115], v[64:65], v[114:115], v[68:69]
	v_lshlrev_b64 v[116:117], 12, v[116:117]
	v_cvt_pk_bf16_f32 v114, v114, v115
	v_cvt_pk_bf16_f32 v115, v112, v113
	v_lshl_add_u32 v112, v212, 2, s0
	ds_read_b32 v112, v112
	global_store_dwordx2 v[130:131], v[114:115], off offset:288
	v_lshl_add_u64 v[114:115], s[2:3], 0, v[212:213]
	v_lshl_add_u64 v[116:117], v[162:163], 0, v[116:117]
	v_lshlrev_b64 v[114:115], 11, v[114:115]
	v_lshl_add_u64 v[114:115], s[18:19], 0, v[114:115]
	v_lshl_add_u64 v[114:115], v[114:115], 0, v[164:165]
	s_waitcnt lgkmcnt(0)
	v_pk_mul_f32 v[98:99], v[98:99], v[112:113] op_sel_hi:[1,0]
	v_pk_mul_f32 v[96:97], v[96:97], v[112:113] op_sel_hi:[1,0]
	v_pk_fma_f32 v[98:99], v[90:91], v[98:99], v[94:95]
	v_pk_fma_f32 v[96:97], v[88:89], v[96:97], v[92:93]
	s_nop 0
	v_cvt_pk_bf16_f32 v96, v96, v97
	v_cvt_pk_bf16_f32 v97, v98, v99
	global_store_dwordx2 v[114:115], v[96:97], off
	v_pk_mul_f32 v[96:97], v[102:103], v[112:113] op_sel_hi:[1,0]
	v_pk_mul_f32 v[98:99], v[100:101], v[112:113] op_sel_hi:[1,0]
	v_pk_fma_f32 v[96:97], v[82:83], v[96:97], v[86:87]
	v_pk_fma_f32 v[98:99], v[80:81], v[98:99], v[84:85]
	s_nop 0
	v_cvt_pk_bf16_f32 v98, v98, v99
	v_cvt_pk_bf16_f32 v99, v96, v97
	global_store_dwordx2 v[114:115], v[98:99], off offset:32
	v_pk_mul_f32 v[96:97], v[106:107], v[112:113] op_sel_hi:[1,0]
	v_pk_mul_f32 v[98:99], v[104:105], v[112:113] op_sel_hi:[1,0]
	v_pk_fma_f32 v[96:97], v[74:75], v[96:97], v[78:79]
	v_pk_fma_f32 v[98:99], v[72:73], v[98:99], v[76:77]
	s_nop 0
	v_cvt_pk_bf16_f32 v98, v98, v99
	v_cvt_pk_bf16_f32 v99, v96, v97
	global_store_dwordx2 v[114:115], v[98:99], off offset:256
	v_pk_mul_f32 v[96:97], v[110:111], v[112:113] op_sel_hi:[1,0]
	v_pk_mul_f32 v[98:99], v[108:109], v[112:113] op_sel_hi:[1,0]
	v_pk_fma_f32 v[96:97], v[66:67], v[96:97], v[70:71]
	v_pk_fma_f32 v[98:99], v[64:65], v[98:99], v[68:69]
	s_nop 0
	v_cvt_pk_bf16_f32 v98, v98, v99
	v_cvt_pk_bf16_f32 v99, v96, v97
	global_store_dwordx2 v[114:115], v[98:99], off offset:288
	s_cbranch_vccz .LBB0_121
	s_andn2_b64 vcc, exec, s[46:47]
	s_mov_b64 s[0:1], -1
	s_cbranch_vccnz .LBB0_69
	s_branch .LBB0_122
.LBB0_121:
	v_readlane_b32 s0, v254, 4
	v_lshlrev_b64 v[100:101], 12, v[224:225]
	v_lshl_add_u64 v[100:101], v[162:163], 0, v[100:101]
	v_lshl_add_u32 v96, v200, 2, s0
	ds_read_b32 v96, v96
	s_mov_b64 s[4:5], 0x80000
	v_lshl_add_u64 v[102:103], v[100:101], 0, s[4:5]
	v_add_co_u32_e32 v100, vcc, 0x80000, v100
	v_lshl_add_u64 v[98:99], s[2:3], 0, v[200:201]
	s_nop 0
	v_addc_co_u32_e32 v101, vcc, 0, v101, vcc
	v_lshlrev_b64 v[98:99], 11, v[98:99]
	v_lshl_add_u64 v[98:99], s[18:19], 0, v[98:99]
	v_lshl_add_u64 v[98:99], v[98:99], 0, v[164:165]
	s_waitcnt lgkmcnt(0)
	v_pk_mul_f32 v[62:63], v[62:63], v[96:97] op_sel_hi:[1,0]
	v_pk_mul_f32 v[60:61], v[60:61], v[96:97] op_sel_hi:[1,0]
	v_pk_fma_f32 v[62:63], v[90:91], v[62:63], v[94:95]
	v_pk_fma_f32 v[60:61], v[88:89], v[60:61], v[92:93]
	s_nop 0
	v_cvt_pk_bf16_f32 v60, v60, v61
	v_cvt_pk_bf16_f32 v61, v62, v63
	global_store_dwordx2 v[98:99], v[60:61], off
	s_nop 1
	v_pk_mul_f32 v[58:59], v[58:59], v[96:97] op_sel_hi:[1,0]
	v_pk_mul_f32 v[56:57], v[56:57], v[96:97] op_sel_hi:[1,0]
	v_pk_fma_f32 v[58:59], v[82:83], v[58:59], v[86:87]
	v_pk_fma_f32 v[56:57], v[80:81], v[56:57], v[84:85]
	s_nop 0
	v_cvt_pk_bf16_f32 v56, v56, v57
	v_cvt_pk_bf16_f32 v57, v58, v59
	global_store_dwordx2 v[98:99], v[56:57], off offset:32
	s_nop 1
	v_pk_mul_f32 v[54:55], v[54:55], v[96:97] op_sel_hi:[1,0]
	v_pk_mul_f32 v[52:53], v[52:53], v[96:97] op_sel_hi:[1,0]
	v_pk_fma_f32 v[54:55], v[74:75], v[54:55], v[78:79]
	v_pk_fma_f32 v[52:53], v[72:73], v[52:53], v[76:77]
	s_nop 0
	v_cvt_pk_bf16_f32 v52, v52, v53
	v_cvt_pk_bf16_f32 v53, v54, v55
	global_store_dwordx2 v[98:99], v[52:53], off offset:256
	v_add_u32_e32 v52, 0x90, v224
	v_ashrrev_i32_e32 v53, 31, v52
	v_pk_mul_f32 v[50:51], v[50:51], v[96:97] op_sel_hi:[1,0]
	v_pk_mul_f32 v[48:49], v[48:49], v[96:97] op_sel_hi:[1,0]
	v_pk_fma_f32 v[50:51], v[66:67], v[50:51], v[70:71]
	v_pk_fma_f32 v[48:49], v[64:65], v[48:49], v[68:69]
	v_lshlrev_b64 v[52:53], 12, v[52:53]
	v_cvt_pk_bf16_f32 v48, v48, v49
	v_cvt_pk_bf16_f32 v49, v50, v51
	global_store_dwordx2 v[98:99], v[48:49], off offset:288
	v_lshl_add_u32 v48, v214, 2, s0
	ds_read_b32 v48, v48
	v_lshl_add_u64 v[50:51], s[2:3], 0, v[214:215]
	v_lshl_add_u64 v[52:53], v[162:163], 0, v[52:53]
	v_lshlrev_b64 v[50:51], 11, v[50:51]
	v_lshl_add_u64 v[50:51], s[18:19], 0, v[50:51]
	v_lshl_add_u64 v[50:51], v[50:51], 0, v[164:165]
	s_waitcnt lgkmcnt(0)
	v_pk_mul_f32 v[46:47], v[46:47], v[48:49] op_sel_hi:[1,0]
	v_pk_mul_f32 v[44:45], v[44:45], v[48:49] op_sel_hi:[1,0]
	v_pk_fma_f32 v[46:47], v[90:91], v[46:47], v[94:95]
	v_pk_fma_f32 v[44:45], v[88:89], v[44:45], v[92:93]
	s_nop 0
	v_cvt_pk_bf16_f32 v44, v44, v45
	v_cvt_pk_bf16_f32 v45, v46, v47
	global_store_dwordx2 v[50:51], v[44:45], off
	s_nop 1
	v_pk_mul_f32 v[42:43], v[42:43], v[48:49] op_sel_hi:[1,0]
	v_pk_mul_f32 v[40:41], v[40:41], v[48:49] op_sel_hi:[1,0]
	v_pk_fma_f32 v[42:43], v[82:83], v[42:43], v[86:87]
	v_pk_fma_f32 v[40:41], v[80:81], v[40:41], v[84:85]
	s_nop 0
	v_cvt_pk_bf16_f32 v40, v40, v41
	v_cvt_pk_bf16_f32 v41, v42, v43
	global_store_dwordx2 v[50:51], v[40:41], off offset:32
	s_nop 1
	v_pk_mul_f32 v[38:39], v[38:39], v[48:49] op_sel_hi:[1,0]
	v_pk_mul_f32 v[36:37], v[36:37], v[48:49] op_sel_hi:[1,0]
	v_pk_fma_f32 v[38:39], v[74:75], v[38:39], v[78:79]
	v_pk_fma_f32 v[36:37], v[72:73], v[36:37], v[76:77]
	s_nop 0
	v_cvt_pk_bf16_f32 v36, v36, v37
	v_cvt_pk_bf16_f32 v37, v38, v39
	global_store_dwordx2 v[50:51], v[36:37], off offset:256
	v_add_u32_e32 v36, 0xa0, v224
	v_ashrrev_i32_e32 v37, 31, v36
	v_pk_mul_f32 v[34:35], v[34:35], v[48:49] op_sel_hi:[1,0]
	v_pk_mul_f32 v[32:33], v[32:33], v[48:49] op_sel_hi:[1,0]
	v_pk_fma_f32 v[34:35], v[66:67], v[34:35], v[70:71]
	v_pk_fma_f32 v[32:33], v[64:65], v[32:33], v[68:69]
	v_lshlrev_b64 v[36:37], 12, v[36:37]
	v_cvt_pk_bf16_f32 v32, v32, v33
	v_cvt_pk_bf16_f32 v33, v34, v35
	global_store_dwordx2 v[50:51], v[32:33], off offset:288
	v_lshl_add_u32 v32, v216, 2, s0
	ds_read_b32 v32, v32
	v_lshl_add_u64 v[34:35], s[2:3], 0, v[216:217]
	v_lshl_add_u64 v[36:37], v[162:163], 0, v[36:37]
	v_lshlrev_b64 v[34:35], 11, v[34:35]
	v_lshl_add_u64 v[34:35], s[18:19], 0, v[34:35]
	v_lshl_add_u64 v[34:35], v[34:35], 0, v[164:165]
	s_waitcnt lgkmcnt(0)
	v_pk_mul_f32 v[30:31], v[30:31], v[32:33] op_sel_hi:[1,0]
	v_pk_mul_f32 v[28:29], v[28:29], v[32:33] op_sel_hi:[1,0]
	v_pk_fma_f32 v[30:31], v[90:91], v[30:31], v[94:95]
	v_pk_fma_f32 v[28:29], v[88:89], v[28:29], v[92:93]
	s_nop 0
	v_cvt_pk_bf16_f32 v28, v28, v29
	v_cvt_pk_bf16_f32 v29, v30, v31
	global_store_dwordx2 v[34:35], v[28:29], off
	s_nop 1
	v_pk_mul_f32 v[26:27], v[26:27], v[32:33] op_sel_hi:[1,0]
	v_pk_mul_f32 v[24:25], v[24:25], v[32:33] op_sel_hi:[1,0]
	v_pk_fma_f32 v[26:27], v[82:83], v[26:27], v[86:87]
	v_pk_fma_f32 v[24:25], v[80:81], v[24:25], v[84:85]
	s_nop 0
	v_cvt_pk_bf16_f32 v24, v24, v25
	v_cvt_pk_bf16_f32 v25, v26, v27
	global_store_dwordx2 v[34:35], v[24:25], off offset:32
	s_nop 1
	v_pk_mul_f32 v[22:23], v[22:23], v[32:33] op_sel_hi:[1,0]
	v_pk_mul_f32 v[20:21], v[20:21], v[32:33] op_sel_hi:[1,0]
	v_pk_fma_f32 v[22:23], v[74:75], v[22:23], v[78:79]
	v_pk_fma_f32 v[20:21], v[72:73], v[20:21], v[76:77]
	s_nop 0
	v_cvt_pk_bf16_f32 v20, v20, v21
	v_cvt_pk_bf16_f32 v21, v22, v23
	global_store_dwordx2 v[34:35], v[20:21], off offset:256
	v_add_u32_e32 v20, 0xb0, v224
	v_ashrrev_i32_e32 v21, 31, v20
	v_pk_mul_f32 v[18:19], v[18:19], v[32:33] op_sel_hi:[1,0]
	v_pk_mul_f32 v[16:17], v[16:17], v[32:33] op_sel_hi:[1,0]
	v_pk_fma_f32 v[18:19], v[66:67], v[18:19], v[70:71]
	v_pk_fma_f32 v[16:17], v[64:65], v[16:17], v[68:69]
	v_lshlrev_b64 v[20:21], 12, v[20:21]
	v_cvt_pk_bf16_f32 v16, v16, v17
	v_cvt_pk_bf16_f32 v17, v18, v19
	global_store_dwordx2 v[34:35], v[16:17], off offset:288
	v_lshl_add_u32 v16, v218, 2, s0
	ds_read_b32 v16, v16
	v_lshl_add_u64 v[18:19], s[2:3], 0, v[218:219]
	v_lshl_add_u64 v[20:21], v[162:163], 0, v[20:21]
	v_lshlrev_b64 v[18:19], 11, v[18:19]
	v_lshl_add_u64 v[18:19], s[18:19], 0, v[18:19]
	v_lshl_add_u64 v[18:19], v[18:19], 0, v[164:165]
	s_waitcnt lgkmcnt(0)
	v_pk_mul_f32 v[14:15], v[14:15], v[16:17] op_sel_hi:[1,0]
	v_pk_mul_f32 v[12:13], v[12:13], v[16:17] op_sel_hi:[1,0]
	v_pk_fma_f32 v[14:15], v[90:91], v[14:15], v[94:95]
	v_pk_fma_f32 v[12:13], v[88:89], v[12:13], v[92:93]
	s_nop 0
	v_cvt_pk_bf16_f32 v12, v12, v13
	v_cvt_pk_bf16_f32 v13, v14, v15
	global_store_dwordx2 v[18:19], v[12:13], off
	s_nop 1
	v_pk_mul_f32 v[10:11], v[10:11], v[16:17] op_sel_hi:[1,0]
	v_pk_mul_f32 v[8:9], v[8:9], v[16:17] op_sel_hi:[1,0]
	v_pk_fma_f32 v[10:11], v[82:83], v[10:11], v[86:87]
	v_pk_fma_f32 v[8:9], v[80:81], v[8:9], v[84:85]
	s_nop 0
	v_cvt_pk_bf16_f32 v8, v8, v9
	v_cvt_pk_bf16_f32 v9, v10, v11
	global_store_dwordx2 v[18:19], v[8:9], off offset:32
	s_nop 1
	v_pk_mul_f32 v[6:7], v[6:7], v[16:17] op_sel_hi:[1,0]
	v_pk_mul_f32 v[4:5], v[4:5], v[16:17] op_sel_hi:[1,0]
	v_pk_fma_f32 v[6:7], v[74:75], v[6:7], v[78:79]
	v_pk_fma_f32 v[4:5], v[72:73], v[4:5], v[76:77]
	s_nop 0
	v_cvt_pk_bf16_f32 v4, v4, v5
	v_cvt_pk_bf16_f32 v5, v6, v7
	global_store_dwordx2 v[18:19], v[4:5], off offset:256
	s_nop 1
	v_pk_mul_f32 v[2:3], v[2:3], v[16:17] op_sel_hi:[1,0]
	v_pk_mul_f32 v[0:1], v[0:1], v[16:17] op_sel_hi:[1,0]
	v_pk_fma_f32 v[2:3], v[66:67], v[2:3], v[70:71]
	v_pk_fma_f32 v[0:1], v[64:65], v[0:1], v[68:69]
	s_nop 0
	v_cvt_pk_bf16_f32 v0, v0, v1
	v_cvt_pk_bf16_f32 v1, v2, v3
	global_store_dwordx2 v[18:19], v[0:1], off offset:288
	s_andn2_b64 vcc, exec, s[46:47]
	s_mov_b64 s[0:1], -1
	s_cbranch_vccnz .LBB0_69

.LBB0_657:
	s_or_b64 exec, exec, s[10:11]
	v_readlane_b32 s10, v255, 26
	s_add_u32 s10, s10, s8
	v_readlane_b32 s11, v255, 28
	s_addc_u32 s11, s11, s9
	s_add_u32 s8, s97, s8
	v_lshl_add_u64 v[64:65], s[10:11], 0, v[230:231]
	v_readlane_b32 s10, v255, 22
	s_addc_u32 s9, s10, s9
	v_lshl_add_u64 v[68:69], s[8:9], 0, v[230:231]
	global_load_dwordx4 v[88:91], v[64:65], off
	global_load_dwordx4 v[80:83], v[64:65], off offset:64
	global_load_dwordx4 v[92:95], v[68:69], off
	global_load_dwordx4 v[84:87], v[68:69], off offset:64
	global_load_dwordx4 v[72:75], v[64:65], off offset:512
	s_nop 0
	global_load_dwordx4 v[64:67], v[64:65], off offset:576
	s_nop 0
	global_load_dwordx4 v[76:79], v[68:69], off offset:512
	s_nop 0
	global_load_dwordx4 v[68:71], v[68:69], off offset:576
	v_lshl_add_u64 v[166:167], v[226:227], 2, s[6:7]
	v_lshl_add_u64 v[166:167], v[166:167], 0, v[228:229]
	global_store_dwordx4 v[166:167], v[128:131], off
	global_store_dwordx4 v[166:167], v[132:135], off offset:64
	global_store_dwordx4 v[166:167], v[136:139], off offset:512
	global_store_dwordx4 v[166:167], v[140:143], off offset:576
	s_mov_b32 s98, 0x10000
	s_mov_b32 s99, 0
	v_lshl_add_u64 v[168:169], v[166:167], 0, s[98:99]
	global_store_dwordx4 v[168:169], v[144:147], off
	global_store_dwordx4 v[168:169], v[148:151], off offset:64
	global_store_dwordx4 v[168:169], v[152:155], off offset:512
	global_store_dwordx4 v[168:169], v[156:159], off offset:576
	v_lshl_add_u64 v[168:169], v[168:169], 0, s[98:99]
	global_store_dwordx4 v[168:169], v[112:115], off
	global_store_dwordx4 v[168:169], v[116:119], off offset:64
	global_store_dwordx4 v[168:169], v[120:123], off offset:512
	global_store_dwordx4 v[168:169], v[124:127], off offset:576
	v_lshl_add_u64 v[168:169], v[168:169], 0, s[98:99]
	global_store_dwordx4 v[168:169], v[96:99], off
	global_store_dwordx4 v[168:169], v[100:103], off offset:64
	global_store_dwordx4 v[168:169], v[104:107], off offset:512
	global_store_dwordx4 v[168:169], v[108:111], off offset:576
	s_and_b64 vcc, exec, s[44:45]
	s_cbranch_vccnz .Lx1skip_b
	s_mov_b32 s98, 0x80000
	v_lshl_add_u64 v[166:167], v[166:167], 0, s[98:99]
	global_store_dwordx4 v[166:167], v[60:63], off
	global_store_dwordx4 v[166:167], v[56:59], off offset:64
	global_store_dwordx4 v[166:167], v[52:55], off offset:512
	global_store_dwordx4 v[166:167], v[48:51], off offset:576
	s_mov_b32 s98, 0x10000
	v_lshl_add_u64 v[168:169], v[166:167], 0, s[98:99]
	global_store_dwordx4 v[168:169], v[44:47], off
	global_store_dwordx4 v[168:169], v[40:43], off offset:64
	global_store_dwordx4 v[168:169], v[36:39], off offset:512
	global_store_dwordx4 v[168:169], v[32:35], off offset:576
	v_lshl_add_u64 v[168:169], v[168:169], 0, s[98:99]
	global_store_dwordx4 v[168:169], v[28:31], off
	global_store_dwordx4 v[168:169], v[24:27], off offset:64
	global_store_dwordx4 v[168:169], v[20:23], off offset:512
	global_store_dwordx4 v[168:169], v[16:19], off offset:576
	v_lshl_add_u64 v[168:169], v[168:169], 0, s[98:99]
	global_store_dwordx4 v[168:169], v[12:15], off
	global_store_dwordx4 v[168:169], v[8:11], off offset:64
	global_store_dwordx4 v[168:169], v[4:7], off offset:512
	global_store_dwordx4 v[168:169], v[0:3], off offset:576
.Lx1skip_b:
	s_mov_b64 s[8:9], exec
	v_readlane_b32 s10, v254, 32
	v_readlane_b32 s11, v254, 33
	s_and_b64 s[10:11], s[8:9], s[10:11]
	s_mov_b64 exec, s[10:11]
	s_cbranch_execz .LBB0_662
	v_mov_b32_e32 v160, 0xfffff
	s_branch .LBB0_660

.LBB0_664:
	s_or_b64 exec, exec, s[2:3]
	s_waitcnt vmcnt(0) lgkmcnt(0)
	s_barrier
	ds_read_b32 v160, v249
	v_lshl_add_u64 v[162:163], v[226:227], 2, s[6:7]
	v_lshl_add_u64 v[164:165], s[46:47], 0, v[198:199]
	v_lshl_add_u64 v[168:169], v[162:163], 0, v[228:229]
	v_lshlrev_b64 v[164:165], 11, v[164:165]
	v_lshl_add_u64 v[166:167], s[18:19], 0, v[164:165]
	v_lshlrev_b64 v[164:165], 1, v[226:227]
	s_waitcnt lgkmcnt(0)
	v_pk_mul_f32 v[130:131], v[130:131], v[160:161] op_sel_hi:[1,0]
	v_pk_mul_f32 v[128:129], v[128:129], v[160:161] op_sel_hi:[1,0]
	v_pk_fma_f32 v[130:131], v[90:91], v[130:131], v[94:95]
	v_pk_fma_f32 v[128:129], v[88:89], v[128:129], v[92:93]
	v_lshl_add_u64 v[166:167], v[166:167], 0, v[164:165]
	v_cvt_pk_bf16_f32 v128, v128, v129
	v_cvt_pk_bf16_f32 v129, v130, v131
	global_store_dwordx2 v[166:167], v[128:129], off
	v_pk_mul_f32 v[128:129], v[134:135], v[160:161] op_sel_hi:[1,0]
	v_pk_mul_f32 v[130:131], v[132:133], v[160:161] op_sel_hi:[1,0]
	v_pk_fma_f32 v[128:129], v[82:83], v[128:129], v[86:87]
	v_pk_fma_f32 v[130:131], v[80:81], v[130:131], v[84:85]
	v_readlane_b32 s0, v254, 4
	v_cvt_pk_bf16_f32 v130, v130, v131
	v_cvt_pk_bf16_f32 v131, v128, v129
	global_store_dwordx2 v[166:167], v[130:131], off offset:32
	v_pk_mul_f32 v[128:129], v[138:139], v[160:161] op_sel_hi:[1,0]
	v_pk_mul_f32 v[130:131], v[136:137], v[160:161] op_sel_hi:[1,0]
	v_pk_fma_f32 v[128:129], v[74:75], v[128:129], v[78:79]
	v_pk_fma_f32 v[130:131], v[72:73], v[130:131], v[76:77]
	v_or_b32_e32 v132, 16, v224
	v_cvt_pk_bf16_f32 v130, v130, v131
	v_cvt_pk_bf16_f32 v131, v128, v129
	global_store_dwordx2 v[166:167], v[130:131], off offset:256
	v_pk_mul_f32 v[128:129], v[142:143], v[160:161] op_sel_hi:[1,0]
	v_pk_mul_f32 v[130:131], v[140:141], v[160:161] op_sel_hi:[1,0]
	v_pk_fma_f32 v[128:129], v[66:67], v[128:129], v[70:71]
	v_pk_fma_f32 v[130:131], v[64:65], v[130:131], v[68:69]
	v_ashrrev_i32_e32 v133, 31, v132
	v_cvt_pk_bf16_f32 v130, v130, v131
	v_cvt_pk_bf16_f32 v131, v128, v129
	v_lshl_add_u32 v128, v208, 2, s0
	ds_read_b32 v128, v128
	global_store_dwordx2 v[166:167], v[130:131], off offset:288
	v_lshl_add_u64 v[130:131], s[46:47], 0, v[208:209]
	v_lshlrev_b64 v[130:131], 11, v[130:131]
	v_lshl_add_u64 v[130:131], s[18:19], 0, v[130:131]
	s_waitcnt lgkmcnt(0)
	v_pk_mul_f32 v[134:135], v[146:147], v[128:129] op_sel_hi:[1,0]
	v_pk_mul_f32 v[136:137], v[144:145], v[128:129] op_sel_hi:[1,0]
	v_lshlrev_b64 v[132:133], 12, v[132:133]
	v_pk_fma_f32 v[134:135], v[90:91], v[134:135], v[94:95]
	v_pk_fma_f32 v[136:137], v[88:89], v[136:137], v[92:93]
	v_lshl_add_u64 v[130:131], v[130:131], 0, v[164:165]
	v_lshl_add_u64 v[132:133], v[162:163], 0, v[132:133]
	v_cvt_pk_bf16_f32 v136, v136, v137
	v_cvt_pk_bf16_f32 v137, v134, v135
	global_store_dwordx2 v[130:131], v[136:137], off
	v_pk_mul_f32 v[134:135], v[150:151], v[128:129] op_sel_hi:[1,0]
	v_pk_mul_f32 v[136:137], v[148:149], v[128:129] op_sel_hi:[1,0]
	v_pk_fma_f32 v[134:135], v[82:83], v[134:135], v[86:87]
	v_pk_fma_f32 v[136:137], v[80:81], v[136:137], v[84:85]
	s_and_b64 vcc, exec, s[44:45]
	v_cvt_pk_bf16_f32 v136, v136, v137
	v_cvt_pk_bf16_f32 v137, v134, v135
	global_store_dwordx2 v[130:131], v[136:137], off offset:32
	v_pk_mul_f32 v[134:135], v[154:155], v[128:129] op_sel_hi:[1,0]
	v_pk_mul_f32 v[136:137], v[152:153], v[128:129] op_sel_hi:[1,0]
	v_pk_fma_f32 v[134:135], v[74:75], v[134:135], v[78:79]
	v_pk_fma_f32 v[136:137], v[72:73], v[136:137], v[76:77]
	s_nop 0
	v_cvt_pk_bf16_f32 v136, v136, v137
	v_cvt_pk_bf16_f32 v137, v134, v135
	global_store_dwordx2 v[130:131], v[136:137], off offset:256
	v_pk_mul_f32 v[132:133], v[158:159], v[128:129] op_sel_hi:[1,0]
	v_pk_mul_f32 v[128:129], v[156:157], v[128:129] op_sel_hi:[1,0]
	v_pk_fma_f32 v[132:133], v[66:67], v[132:133], v[70:71]
	v_pk_fma_f32 v[128:129], v[64:65], v[128:129], v[68:69]
	s_nop 0
	v_cvt_pk_bf16_f32 v128, v128, v129
	v_cvt_pk_bf16_f32 v129, v132, v133
	global_store_dwordx2 v[130:131], v[128:129], off offset:288
	v_lshl_add_u32 v128, v210, 2, s0
	ds_read_b32 v128, v128
	v_or_b32_e32 v132, 32, v224
	v_ashrrev_i32_e32 v133, 31, v132
	v_lshlrev_b64 v[132:133], 12, v[132:133]
	v_lshl_add_u64 v[130:131], s[46:47], 0, v[210:211]
	v_lshl_add_u64 v[132:133], v[162:163], 0, v[132:133]
	v_lshlrev_b64 v[130:131], 11, v[130:131]
	v_lshl_add_u64 v[130:131], s[18:19], 0, v[130:131]
	v_lshl_add_u64 v[130:131], v[130:131], 0, v[164:165]
	s_waitcnt lgkmcnt(0)
	v_pk_mul_f32 v[114:115], v[114:115], v[128:129] op_sel_hi:[1,0]
	v_pk_mul_f32 v[112:113], v[112:113], v[128:129] op_sel_hi:[1,0]
	v_pk_fma_f32 v[114:115], v[90:91], v[114:115], v[94:95]
	v_pk_fma_f32 v[112:113], v[88:89], v[112:113], v[92:93]
	s_nop 0
	v_cvt_pk_bf16_f32 v112, v112, v113
	v_cvt_pk_bf16_f32 v113, v114, v115
	global_store_dwordx2 v[130:131], v[112:113], off
	v_pk_mul_f32 v[112:113], v[118:119], v[128:129] op_sel_hi:[1,0]
	v_pk_mul_f32 v[114:115], v[116:117], v[128:129] op_sel_hi:[1,0]
	v_pk_fma_f32 v[112:113], v[82:83], v[112:113], v[86:87]
	v_pk_fma_f32 v[114:115], v[80:81], v[114:115], v[84:85]
	v_or_b32_e32 v116, 48, v224
	v_cvt_pk_bf16_f32 v114, v114, v115
	v_cvt_pk_bf16_f32 v115, v112, v113
	global_store_dwordx2 v[130:131], v[114:115], off offset:32
	v_pk_mul_f32 v[112:113], v[122:123], v[128:129] op_sel_hi:[1,0]
	v_pk_mul_f32 v[114:115], v[120:121], v[128:129] op_sel_hi:[1,0]
	v_pk_fma_f32 v[112:113], v[74:75], v[112:113], v[78:79]
	v_pk_fma_f32 v[114:115], v[72:73], v[114:115], v[76:77]
	v_ashrrev_i32_e32 v117, 31, v116
	v_cvt_pk_bf16_f32 v114, v114, v115
	v_cvt_pk_bf16_f32 v115, v112, v113
	global_store_dwordx2 v[130:131], v[114:115], off offset:256
	v_pk_mul_f32 v[112:113], v[126:127], v[128:129] op_sel_hi:[1,0]
	v_pk_mul_f32 v[114:115], v[124:125], v[128:129] op_sel_hi:[1,0]
	v_pk_fma_f32 v[112:113], v[66:67], v[112:113], v[70:71]
	v_pk_fma_f32 v[114:115], v[64:65], v[114:115], v[68:69]
	v_lshlrev_b64 v[116:117], 12, v[116:117]
	v_cvt_pk_bf16_f32 v114, v114, v115
	v_cvt_pk_bf16_f32 v115, v112, v113
	v_lshl_add_u32 v112, v212, 2, s0
	ds_read_b32 v112, v112
	global_store_dwordx2 v[130:131], v[114:115], off offset:288
	v_lshl_add_u64 v[114:115], s[46:47], 0, v[212:213]
	v_lshl_add_u64 v[116:117], v[162:163], 0, v[116:117]
	v_lshlrev_b64 v[114:115], 11, v[114:115]
	v_lshl_add_u64 v[114:115], s[18:19], 0, v[114:115]
	v_lshl_add_u64 v[114:115], v[114:115], 0, v[164:165]
	s_waitcnt lgkmcnt(0)
	v_pk_mul_f32 v[98:99], v[98:99], v[112:113] op_sel_hi:[1,0]
	v_pk_mul_f32 v[96:97], v[96:97], v[112:113] op_sel_hi:[1,0]
	v_pk_fma_f32 v[98:99], v[90:91], v[98:99], v[94:95]
	v_pk_fma_f32 v[96:97], v[88:89], v[96:97], v[92:93]
	s_nop 0
	v_cvt_pk_bf16_f32 v96, v96, v97
	v_cvt_pk_bf16_f32 v97, v98, v99
	global_store_dwordx2 v[114:115], v[96:97], off
	v_pk_mul_f32 v[96:97], v[102:103], v[112:113] op_sel_hi:[1,0]
	v_pk_mul_f32 v[98:99], v[100:101], v[112:113] op_sel_hi:[1,0]
	v_pk_fma_f32 v[96:97], v[82:83], v[96:97], v[86:87]
	v_pk_fma_f32 v[98:99], v[80:81], v[98:99], v[84:85]
	s_nop 0
	v_cvt_pk_bf16_f32 v98, v98, v99
	v_cvt_pk_bf16_f32 v99, v96, v97
	global_store_dwordx2 v[114:115], v[98:99], off offset:32
	v_pk_mul_f32 v[96:97], v[106:107], v[112:113] op_sel_hi:[1,0]
	v_pk_mul_f32 v[98:99], v[104:105], v[112:113] op_sel_hi:[1,0]
	v_pk_fma_f32 v[96:97], v[74:75], v[96:97], v[78:79]
	v_pk_fma_f32 v[98:99], v[72:73], v[98:99], v[76:77]
	s_nop 0
	v_cvt_pk_bf16_f32 v98, v98, v99
	v_cvt_pk_bf16_f32 v99, v96, v97
	global_store_dwordx2 v[114:115], v[98:99], off offset:256
	v_pk_mul_f32 v[96:97], v[110:111], v[112:113] op_sel_hi:[1,0]
	v_pk_mul_f32 v[98:99], v[108:109], v[112:113] op_sel_hi:[1,0]
	v_pk_fma_f32 v[96:97], v[66:67], v[96:97], v[70:71]
	v_pk_fma_f32 v[98:99], v[64:65], v[98:99], v[68:69]
	s_nop 0
	v_cvt_pk_bf16_f32 v98, v98, v99
	v_cvt_pk_bf16_f32 v99, v96, v97
	global_store_dwordx2 v[114:115], v[98:99], off offset:288
	s_cbranch_vccz .LBB0_666
	s_and_b64 vcc, exec, s[42:43]
	s_mov_b64 s[0:1], -1
	s_cbranch_vccnz .LBB0_610
	s_branch .LBB0_667
.LBB0_666:
	v_readlane_b32 s0, v254, 4
	v_lshlrev_b64 v[100:101], 12, v[224:225]
	v_lshl_add_u64 v[100:101], v[162:163], 0, v[100:101]
	v_lshl_add_u32 v96, v200, 2, s0
	ds_read_b32 v96, v96
	s_mov_b64 s[2:3], 0x80000
	v_lshl_add_u64 v[102:103], v[100:101], 0, s[2:3]
	v_add_co_u32_e32 v100, vcc, 0x80000, v100
	v_lshl_add_u64 v[98:99], s[46:47], 0, v[200:201]
	s_nop 0
	v_addc_co_u32_e32 v101, vcc, 0, v101, vcc
	v_lshlrev_b64 v[98:99], 11, v[98:99]
	v_lshl_add_u64 v[98:99], s[18:19], 0, v[98:99]
	v_lshl_add_u64 v[98:99], v[98:99], 0, v[164:165]
	s_waitcnt lgkmcnt(0)
	v_pk_mul_f32 v[62:63], v[62:63], v[96:97] op_sel_hi:[1,0]
	v_pk_mul_f32 v[60:61], v[60:61], v[96:97] op_sel_hi:[1,0]
	v_pk_fma_f32 v[62:63], v[90:91], v[62:63], v[94:95]
	v_pk_fma_f32 v[60:61], v[88:89], v[60:61], v[92:93]
	s_nop 0
	v_cvt_pk_bf16_f32 v60, v60, v61
	v_cvt_pk_bf16_f32 v61, v62, v63
	global_store_dwordx2 v[98:99], v[60:61], off
	s_nop 1
	v_pk_mul_f32 v[58:59], v[58:59], v[96:97] op_sel_hi:[1,0]
	v_pk_mul_f32 v[56:57], v[56:57], v[96:97] op_sel_hi:[1,0]
	v_pk_fma_f32 v[58:59], v[82:83], v[58:59], v[86:87]
	v_pk_fma_f32 v[56:57], v[80:81], v[56:57], v[84:85]
	s_nop 0
	v_cvt_pk_bf16_f32 v56, v56, v57
	v_cvt_pk_bf16_f32 v57, v58, v59
	global_store_dwordx2 v[98:99], v[56:57], off offset:32
	s_nop 1
	v_pk_mul_f32 v[54:55], v[54:55], v[96:97] op_sel_hi:[1,0]
	v_pk_mul_f32 v[52:53], v[52:53], v[96:97] op_sel_hi:[1,0]
	v_pk_fma_f32 v[54:55], v[74:75], v[54:55], v[78:79]
	v_pk_fma_f32 v[52:53], v[72:73], v[52:53], v[76:77]
	s_nop 0
	v_cvt_pk_bf16_f32 v52, v52, v53
	v_cvt_pk_bf16_f32 v53, v54, v55
	global_store_dwordx2 v[98:99], v[52:53], off offset:256
	v_add_u32_e32 v52, 0x90, v224
	v_ashrrev_i32_e32 v53, 31, v52
	v_pk_mul_f32 v[50:51], v[50:51], v[96:97] op_sel_hi:[1,0]
	v_pk_mul_f32 v[48:49], v[48:49], v[96:97] op_sel_hi:[1,0]
	v_pk_fma_f32 v[50:51], v[66:67], v[50:51], v[70:71]
	v_pk_fma_f32 v[48:49], v[64:65], v[48:49], v[68:69]
	v_lshlrev_b64 v[52:53], 12, v[52:53]
	v_cvt_pk_bf16_f32 v48, v48, v49
	v_cvt_pk_bf16_f32 v49, v50, v51
	global_store_dwordx2 v[98:99], v[48:49], off offset:288
	v_lshl_add_u32 v48, v214, 2, s0
	ds_read_b32 v48, v48
	v_lshl_add_u64 v[50:51], s[46:47], 0, v[214:215]
	v_lshl_add_u64 v[52:53], v[162:163], 0, v[52:53]
	v_lshlrev_b64 v[50:51], 11, v[50:51]
	v_lshl_add_u64 v[50:51], s[18:19], 0, v[50:51]
	v_lshl_add_u64 v[50:51], v[50:51], 0, v[164:165]
	s_waitcnt lgkmcnt(0)
	v_pk_mul_f32 v[46:47], v[46:47], v[48:49] op_sel_hi:[1,0]
	v_pk_mul_f32 v[44:45], v[44:45], v[48:49] op_sel_hi:[1,0]
	v_pk_fma_f32 v[46:47], v[90:91], v[46:47], v[94:95]
	v_pk_fma_f32 v[44:45], v[88:89], v[44:45], v[92:93]
	s_nop 0
	v_cvt_pk_bf16_f32 v44, v44, v45
	v_cvt_pk_bf16_f32 v45, v46, v47
	global_store_dwordx2 v[50:51], v[44:45], off
	s_nop 1
	v_pk_mul_f32 v[42:43], v[42:43], v[48:49] op_sel_hi:[1,0]
	v_pk_mul_f32 v[40:41], v[40:41], v[48:49] op_sel_hi:[1,0]
	v_pk_fma_f32 v[42:43], v[82:83], v[42:43], v[86:87]
	v_pk_fma_f32 v[40:41], v[80:81], v[40:41], v[84:85]
	s_nop 0
	v_cvt_pk_bf16_f32 v40, v40, v41
	v_cvt_pk_bf16_f32 v41, v42, v43
	global_store_dwordx2 v[50:51], v[40:41], off offset:32
	s_nop 1
	v_pk_mul_f32 v[38:39], v[38:39], v[48:49] op_sel_hi:[1,0]
	v_pk_mul_f32 v[36:37], v[36:37], v[48:49] op_sel_hi:[1,0]
	v_pk_fma_f32 v[38:39], v[74:75], v[38:39], v[78:79]
	v_pk_fma_f32 v[36:37], v[72:73], v[36:37], v[76:77]
	s_nop 0
	v_cvt_pk_bf16_f32 v36, v36, v37
	v_cvt_pk_bf16_f32 v37, v38, v39
	global_store_dwordx2 v[50:51], v[36:37], off offset:256
	v_add_u32_e32 v36, 0xa0, v224
	v_ashrrev_i32_e32 v37, 31, v36
	v_pk_mul_f32 v[34:35], v[34:35], v[48:49] op_sel_hi:[1,0]
	v_pk_mul_f32 v[32:33], v[32:33], v[48:49] op_sel_hi:[1,0]
	v_pk_fma_f32 v[34:35], v[66:67], v[34:35], v[70:71]
	v_pk_fma_f32 v[32:33], v[64:65], v[32:33], v[68:69]
	v_lshlrev_b64 v[36:37], 12, v[36:37]
	v_cvt_pk_bf16_f32 v32, v32, v33
	v_cvt_pk_bf16_f32 v33, v34, v35
	global_store_dwordx2 v[50:51], v[32:33], off offset:288
	v_lshl_add_u32 v32, v216, 2, s0
	ds_read_b32 v32, v32
	v_lshl_add_u64 v[34:35], s[46:47], 0, v[216:217]
	v_lshl_add_u64 v[36:37], v[162:163], 0, v[36:37]
	v_lshlrev_b64 v[34:35], 11, v[34:35]
	v_lshl_add_u64 v[34:35], s[18:19], 0, v[34:35]
	v_lshl_add_u64 v[34:35], v[34:35], 0, v[164:165]
	s_waitcnt lgkmcnt(0)
	v_pk_mul_f32 v[30:31], v[30:31], v[32:33] op_sel_hi:[1,0]
	v_pk_mul_f32 v[28:29], v[28:29], v[32:33] op_sel_hi:[1,0]
	v_pk_fma_f32 v[30:31], v[90:91], v[30:31], v[94:95]
	v_pk_fma_f32 v[28:29], v[88:89], v[28:29], v[92:93]
	s_nop 0
	v_cvt_pk_bf16_f32 v28, v28, v29
	v_cvt_pk_bf16_f32 v29, v30, v31
	global_store_dwordx2 v[34:35], v[28:29], off
	s_nop 1
	v_pk_mul_f32 v[26:27], v[26:27], v[32:33] op_sel_hi:[1,0]
	v_pk_mul_f32 v[24:25], v[24:25], v[32:33] op_sel_hi:[1,0]
	v_pk_fma_f32 v[26:27], v[82:83], v[26:27], v[86:87]
	v_pk_fma_f32 v[24:25], v[80:81], v[24:25], v[84:85]
	s_nop 0
	v_cvt_pk_bf16_f32 v24, v24, v25
	v_cvt_pk_bf16_f32 v25, v26, v27
	global_store_dwordx2 v[34:35], v[24:25], off offset:32
	s_nop 1
	v_pk_mul_f32 v[22:23], v[22:23], v[32:33] op_sel_hi:[1,0]
	v_pk_mul_f32 v[20:21], v[20:21], v[32:33] op_sel_hi:[1,0]
	v_pk_fma_f32 v[22:23], v[74:75], v[22:23], v[78:79]
	v_pk_fma_f32 v[20:21], v[72:73], v[20:21], v[76:77]
	s_nop 0
	v_cvt_pk_bf16_f32 v20, v20, v21
	v_cvt_pk_bf16_f32 v21, v22, v23
	global_store_dwordx2 v[34:35], v[20:21], off offset:256
	v_add_u32_e32 v20, 0xb0, v224
	v_ashrrev_i32_e32 v21, 31, v20
	v_pk_mul_f32 v[18:19], v[18:19], v[32:33] op_sel_hi:[1,0]
	v_pk_mul_f32 v[16:17], v[16:17], v[32:33] op_sel_hi:[1,0]
	v_pk_fma_f32 v[18:19], v[66:67], v[18:19], v[70:71]
	v_pk_fma_f32 v[16:17], v[64:65], v[16:17], v[68:69]
	v_lshlrev_b64 v[20:21], 12, v[20:21]
	v_cvt_pk_bf16_f32 v16, v16, v17
	v_cvt_pk_bf16_f32 v17, v18, v19
	global_store_dwordx2 v[34:35], v[16:17], off offset:288
	v_lshl_add_u32 v16, v218, 2, s0
	ds_read_b32 v16, v16
	v_lshl_add_u64 v[18:19], s[46:47], 0, v[218:219]
	v_lshl_add_u64 v[20:21], v[162:163], 0, v[20:21]
	v_lshlrev_b64 v[18:19], 11, v[18:19]
	v_lshl_add_u64 v[18:19], s[18:19], 0, v[18:19]
	v_lshl_add_u64 v[18:19], v[18:19], 0, v[164:165]
	s_waitcnt lgkmcnt(0)
	v_pk_mul_f32 v[14:15], v[14:15], v[16:17] op_sel_hi:[1,0]
	v_pk_mul_f32 v[12:13], v[12:13], v[16:17] op_sel_hi:[1,0]
	v_pk_fma_f32 v[14:15], v[90:91], v[14:15], v[94:95]
	v_pk_fma_f32 v[12:13], v[88:89], v[12:13], v[92:93]
	s_nop 0
	v_cvt_pk_bf16_f32 v12, v12, v13
	v_cvt_pk_bf16_f32 v13, v14, v15
	global_store_dwordx2 v[18:19], v[12:13], off
	s_nop 1
	v_pk_mul_f32 v[10:11], v[10:11], v[16:17] op_sel_hi:[1,0]
	v_pk_mul_f32 v[8:9], v[8:9], v[16:17] op_sel_hi:[1,0]
	v_pk_fma_f32 v[10:11], v[82:83], v[10:11], v[86:87]
	v_pk_fma_f32 v[8:9], v[80:81], v[8:9], v[84:85]
	s_nop 0
	v_cvt_pk_bf16_f32 v8, v8, v9
	v_cvt_pk_bf16_f32 v9, v10, v11
	global_store_dwordx2 v[18:19], v[8:9], off offset:32
	s_nop 1
	v_pk_mul_f32 v[6:7], v[6:7], v[16:17] op_sel_hi:[1,0]
	v_pk_mul_f32 v[4:5], v[4:5], v[16:17] op_sel_hi:[1,0]
	v_pk_fma_f32 v[6:7], v[74:75], v[6:7], v[78:79]
	v_pk_fma_f32 v[4:5], v[72:73], v[4:5], v[76:77]
	s_nop 0
	v_cvt_pk_bf16_f32 v4, v4, v5
	v_cvt_pk_bf16_f32 v5, v6, v7
	global_store_dwordx2 v[18:19], v[4:5], off offset:256
	s_nop 1
	v_pk_mul_f32 v[2:3], v[2:3], v[16:17] op_sel_hi:[1,0]
	v_pk_mul_f32 v[0:1], v[0:1], v[16:17] op_sel_hi:[1,0]
	v_pk_fma_f32 v[2:3], v[66:67], v[2:3], v[70:71]
	v_pk_fma_f32 v[0:1], v[64:65], v[0:1], v[68:69]
	s_nop 0
	v_cvt_pk_bf16_f32 v0, v0, v1
	v_cvt_pk_bf16_f32 v1, v2, v3
	global_store_dwordx2 v[18:19], v[0:1], off offset:288
	s_and_b64 vcc, exec, s[42:43]
	s_mov_b64 s[0:1], -1
	s_cbranch_vccnz .LBB0_610
